# forgetting / stick-breaking loops: the two done-flag LDS reads after each step barrier issued back-to-back under one wait
# speedup vs baseline: 1.0044x; 1.0044x over previous
; #define WAIT_OLD(S) do { if (TYPE == 2) asm volatile("s_waitcnt vmcnt(4)" : "+v"(rk0##S), "+v"(rk1##S), "+v"(rv0##S), "+v"(rv1##S), "+v"(rkr##S), "+v"(rck##S)); \
;         else asm volatile("s_waitcnt vmcnt(5)" : "+v"(rk0##S), "+v"(rk1##S), "+v"(rv0##S), "+v"(rv1##S), "+v"(rkr##S), "+v"(rck##S)); } while (0)
; #define SB_FLAGS(N_) do { if (TYPE != 1) { if (TYPE == 2) wdone = (__all(carry < -170.f) != 0); if (lane == 0) flags[((N_) & 1) * 8 + w8] = wdone ? 1u : 0u; } } while (0)
; template <int TYPE>
; DI void attn_item(KargPtr p, int b, int h, int qb, unsigned char* smem) {
;     ...
;         WAIT_OLD(A);
;         STORE_TILE(A, 1);
;         SB_FLAGS(n);
;         __syncthreads();
;         if (SB_DONE(n)) break;
;         if (n + 1 >= ntiles) break;
;         LOAD_TILE(A, TILE_OF(n + 3));
.LBB0_576:
	s_or_b64 exec, exec, s[82:83]
	v_cmp_gt_f32_e32 vcc, s60, v164
	s_waitcnt vmcnt(4)
	v_add_u32_e32 v0, 0x6800, v214
	s_cmp_eq_u64 vcc, exec
	ds_write_b128 v212, v[106:109] offset:18688
	ds_write_b128 v213, v[110:113] offset:18688
	ds_write2_b64 v0, v[114:115], v[116:117] offset0:160 offset1:162
	v_add_u32_e32 v0, 0x6800, v216
	s_cselect_b64 s[8:9], -1, 0
	ds_write2_b64 v0, v[118:119], v[120:121] offset0:160 offset1:162
	s_and_saveexec_b64 s[10:11], s[6:7]
	v_cndmask_b32_e64 v0, 0, 1, s[8:9]
	ds_write_b32 v222, v0
	s_or_b64 exec, exec, s[10:11]
	v_mov_b32_e32 v0, s86
	s_waitcnt lgkmcnt(0)
	s_barrier
	ds_read_b128 v[4:7], v0
	v_mov_b32_e32 v1, s77
	ds_read_b128 v[226:229], v1
	s_waitcnt lgkmcnt(0)
	v_and_b32_e32 v0, v5, v4
	v_and_b32_e32 v0, v0, v6
	v_and_b32_e32 v0, v0, v7
	s_waitcnt lgkmcnt(0)
	v_and_b32_e32 v0, v0, v226
	v_and_b32_e32 v0, v0, v227
	v_and_b32_e32 v0, v0, v228
	v_and_b32_e32 v0, v0, v229
	v_cmp_ne_u32_e32 vcc, 0, v0
	s_cbranch_vccnz .LBB0_571
	s_add_i32 s33, s78, 3
	s_cmp_lt_u32 s33, s76
	s_cselect_b32 s10, s2, 0
	v_add_u32_e32 v0, s10, v157
	v_ashrrev_i32_e32 v1, 31, v0
	v_lshlrev_b64 v[0:1], 10, v[0:1]
	v_lshl_add_u64 v[0:1], s[72:73], 0, v[0:1]
	v_lshl_add_u64 v[0:1], v[0:1], 0, v[2:3]
	global_load_dwordx4 v[106:109], v[0:1], off
	v_add_u32_e32 v0, s10, v211
	v_ashrrev_i32_e32 v1, 31, v0
	s_ashr_i32 s11, s10, 31
	v_lshlrev_b64 v[0:1], 10, v[0:1]
	s_lshl_b64 s[10:11], s[10:11], 7
	v_lshl_add_u64 v[0:1], s[72:73], 0, v[0:1]
	s_add_u32 s10, s87, s10
	v_lshl_add_u64 v[0:1], v[0:1], 0, v[2:3]
	s_addc_u32 s11, s75, s11
	global_load_dwordx4 v[110:113], v[0:1], off
	v_lshl_add_u64 v[0:1], v[160:161], 1, s[10:11]
	v_lshl_add_u64 v[0:1], v[0:1], 0, v[2:3]
	global_load_dwordx4 v[114:117], v[0:1], off
	v_lshl_add_u64 v[0:1], v[162:163], 1, s[10:11]
	v_lshl_add_u64 v[0:1], v[0:1], 0, v[2:3]
	global_load_dwordx4 v[118:121], v[0:1], off
	s_add_i32 s10, s2, 0x80
	v_cmp_le_i32_e32 vcc, s10, v219
	s_xor_b64 s[8:9], s[8:9], -1
	s_and_b64 s[8:9], vcc, s[8:9]
	s_and_saveexec_b64 s[82:83], s[8:9]
	s_cbranch_execz .LBB0_583
	v_add_u32_e32 v224, v220, v156
	ds_read_b128 v[4:7], v224 offset:18688
	ds_read_b128 v[8:11], v224 offset:18720
	s_add_i32 s8, s2, 0xbf
	v_cmp_ge_i32_e32 vcc, s8, v159
	s_waitcnt lgkmcnt(1)
	v_mfma_f32_32x32x16_bf16 v[50:65], v[4:7], v[86:89], 0
	ds_read_b128 v[4:7], v224 offset:23296
	ds_read_b128 v[12:15], v224 offset:23328
	s_waitcnt lgkmcnt(1)
	v_mfma_f32_32x32x16_bf16 v[66:81], v[4:7], v[86:89], 0
	s_nop 0
	v_mfma_f32_32x32x16_bf16 v[50:65], v[8:11], v[90:93], v[50:65]
	ds_read_b128 v[4:7], v224 offset:18752
	ds_read_b128 v[8:11], v224 offset:18784
	s_waitcnt lgkmcnt(2)
	v_mfma_f32_32x32x16_bf16 v[66:81], v[12:15], v[90:93], v[66:81]
	s_waitcnt lgkmcnt(1)
	v_mfma_f32_32x32x16_bf16 v[50:65], v[4:7], v[94:97], v[50:65]
	ds_read_b128 v[4:7], v224 offset:23360
	ds_read_b128 v[12:15], v224 offset:23392
	s_waitcnt lgkmcnt(1)
	v_mfma_f32_32x32x16_bf16 v[66:81], v[4:7], v[94:97], v[66:81]
	s_waitcnt lgkmcnt(0)
	v_mfma_f32_32x32x16_bf16 v[66:81], v[12:15], v[98:101], v[66:81]
	v_mfma_f32_32x32x16_bf16 v[50:65], v[8:11], v[98:101], v[50:65]
	s_nop 10
	v_exp_f32_e64 v1, -|v66|
	s_nop 0
	v_add_f32_e32 v1, 1.0, v1
	v_log_f32_e32 v6, v1
	v_max_f32_e32 v1, v66, v66
	v_max_f32_e32 v2, v50, v50
	v_exp_f32_e64 v0, -|v50|
	v_min_f32_e32 v4, 0, v2
	v_exp_f32_e64 v2, -|v51|
	v_min_f32_e32 v8, 0, v1
	v_add_f32_e32 v0, 1.0, v0
	v_log_f32_e32 v0, v0
	v_add_f32_e32 v1, 1.0, v2
	v_log_f32_e32 v1, v1
	v_exp_f32_e64 v2, -|v67|
	v_max_f32_e32 v5, v51, v51
	v_min_f32_e32 v5, 0, v5
	v_pk_add_f32 v[166:167], v[4:5], v[0:1] neg_lo:[0,1] neg_hi:[0,1]
	v_max_f32_e32 v1, v67, v67
	v_add_f32_e32 v0, 1.0, v2
	v_min_f32_e32 v9, 0, v1
	v_exp_f32_e64 v1, -|v68|
	v_log_f32_e32 v7, v0
	v_max_f32_e32 v2, v52, v52
	v_exp_f32_e64 v0, -|v52|
	v_min_f32_e32 v4, 0, v2
	v_exp_f32_e64 v2, -|v53|
	v_add_f32_e32 v1, 1.0, v1
	v_pk_add_f32 v[180:181], v[8:9], v[6:7] neg_lo:[0,1] neg_hi:[0,1]
	v_log_f32_e32 v6, v1
	v_max_f32_e32 v1, v68, v68
	v_add_f32_e32 v0, 1.0, v0
	v_min_f32_e32 v8, 0, v1
	v_add_f32_e32 v1, 1.0, v2
	v_log_f32_e32 v0, v0
	v_log_f32_e32 v1, v1
	v_exp_f32_e64 v2, -|v69|
	v_max_f32_e32 v5, v53, v53
	v_min_f32_e32 v5, 0, v5
	v_pk_add_f32 v[168:169], v[4:5], v[0:1] neg_lo:[0,1] neg_hi:[0,1]
	v_max_f32_e32 v1, v69, v69
	v_add_f32_e32 v0, 1.0, v2
	v_min_f32_e32 v9, 0, v1
	v_exp_f32_e64 v1, -|v70|
	v_log_f32_e32 v7, v0
	v_max_f32_e32 v2, v54, v54
	v_exp_f32_e64 v0, -|v54|
	v_min_f32_e32 v4, 0, v2
	v_exp_f32_e64 v2, -|v55|
	v_add_f32_e32 v1, 1.0, v1
	v_pk_add_f32 v[184:185], v[8:9], v[6:7] neg_lo:[0,1] neg_hi:[0,1]
	v_log_f32_e32 v6, v1
	v_max_f32_e32 v1, v70, v70
	v_add_f32_e32 v0, 1.0, v0
	v_min_f32_e32 v8, 0, v1
	v_add_f32_e32 v1, 1.0, v2
	v_log_f32_e32 v0, v0
	v_log_f32_e32 v1, v1
	v_exp_f32_e64 v2, -|v71|
	v_max_f32_e32 v5, v55, v55
	v_min_f32_e32 v5, 0, v5
	v_pk_add_f32 v[170:171], v[4:5], v[0:1] neg_lo:[0,1] neg_hi:[0,1]
	v_max_f32_e32 v1, v71, v71
	v_add_f32_e32 v0, 1.0, v2
	v_min_f32_e32 v9, 0, v1
	v_exp_f32_e64 v1, -|v72|
	v_log_f32_e32 v7, v0
	v_max_f32_e32 v2, v56, v56
	v_exp_f32_e64 v0, -|v56|
	v_min_f32_e32 v4, 0, v2
	v_exp_f32_e64 v2, -|v57|
	v_add_f32_e32 v1, 1.0, v1
	v_pk_add_f32 v[186:187], v[8:9], v[6:7] neg_lo:[0,1] neg_hi:[0,1]
	v_log_f32_e32 v6, v1
	v_max_f32_e32 v1, v72, v72
	v_add_f32_e32 v0, 1.0, v0
	v_min_f32_e32 v8, 0, v1
	v_add_f32_e32 v1, 1.0, v2
	v_log_f32_e32 v0, v0
	v_log_f32_e32 v1, v1
	v_exp_f32_e64 v2, -|v73|
	v_max_f32_e32 v5, v57, v57
	v_min_f32_e32 v5, 0, v5
	v_pk_add_f32 v[172:173], v[4:5], v[0:1] neg_lo:[0,1] neg_hi:[0,1]
	v_max_f32_e32 v1, v73, v73
	v_add_f32_e32 v0, 1.0, v2
	v_min_f32_e32 v9, 0, v1
; DI float fexp2(float x) { return __builtin_amdgcn_exp2f(x); }
; DI float flog2(float x) { return __builtin_amdgcn_logf(x); }
; template <int TYPE>
; DI void attn_item(KargPtr p, int b, int h, int qb, unsigned char* smem) {
;     ...
;                 float lk0[16], lk1[16];
; #pragma unroll
;                 for (int i = 0; i < 16; ++i) {
;                     {
;                         const float z = s0[i]; const float sp = flog2(1.0f + fexp2(-fabsf(z)));
;                         const float lb = fminf(z, 0.f) - sp;
;                         s0[i] = lb; lk0[i] = lb - z;
;                     }
;                     {
;                         const float z = s1[i]; const float sp = flog2(1.0f + fexp2(-fabsf(z)));
;                         const float lb = fminf(z, 0.f) - sp;
;                         s1[i] = lb; lk1[i] = lb - z;
;                     }
;                 }
	v_exp_f32_e64 v1, -|v74|
	v_log_f32_e32 v7, v0
	v_max_f32_e32 v2, v58, v58
	v_exp_f32_e64 v0, -|v58|
	v_min_f32_e32 v4, 0, v2
	v_exp_f32_e64 v2, -|v59|
	v_add_f32_e32 v1, 1.0, v1
	v_pk_add_f32 v[188:189], v[8:9], v[6:7] neg_lo:[0,1] neg_hi:[0,1]
	v_log_f32_e32 v6, v1
	v_max_f32_e32 v1, v74, v74
	v_add_f32_e32 v0, 1.0, v0
	v_min_f32_e32 v8, 0, v1
	v_add_f32_e32 v1, 1.0, v2
	v_log_f32_e32 v0, v0
	v_log_f32_e32 v1, v1
	v_exp_f32_e64 v2, -|v75|
	v_max_f32_e32 v5, v59, v59
	v_min_f32_e32 v5, 0, v5
	v_pk_add_f32 v[174:175], v[4:5], v[0:1] neg_lo:[0,1] neg_hi:[0,1]
	v_max_f32_e32 v1, v75, v75
	v_add_f32_e32 v0, 1.0, v2
	v_min_f32_e32 v9, 0, v1
	v_exp_f32_e64 v1, -|v76|
	v_log_f32_e32 v7, v0
	v_max_f32_e32 v2, v60, v60
	v_exp_f32_e64 v0, -|v60|
	v_min_f32_e32 v4, 0, v2
	v_exp_f32_e64 v2, -|v61|
	v_add_f32_e32 v1, 1.0, v1
	v_pk_add_f32 v[190:191], v[8:9], v[6:7] neg_lo:[0,1] neg_hi:[0,1]
	v_log_f32_e32 v6, v1
	v_max_f32_e32 v1, v76, v76
	v_add_f32_e32 v0, 1.0, v0
	v_min_f32_e32 v8, 0, v1
	v_add_f32_e32 v1, 1.0, v2
	v_log_f32_e32 v0, v0
	v_log_f32_e32 v1, v1
	v_exp_f32_e64 v2, -|v77|
	v_max_f32_e32 v5, v61, v61
	v_min_f32_e32 v5, 0, v5
	v_pk_add_f32 v[176:177], v[4:5], v[0:1] neg_lo:[0,1] neg_hi:[0,1]
	v_max_f32_e32 v1, v77, v77
	v_add_f32_e32 v0, 1.0, v2
	v_min_f32_e32 v9, 0, v1
	v_exp_f32_e64 v1, -|v78|
	v_log_f32_e32 v7, v0
	v_max_f32_e32 v2, v62, v62
	v_exp_f32_e64 v0, -|v62|
	v_min_f32_e32 v4, 0, v2
	v_exp_f32_e64 v2, -|v63|
	v_add_f32_e32 v1, 1.0, v1
	v_pk_add_f32 v[192:193], v[8:9], v[6:7] neg_lo:[0,1] neg_hi:[0,1]
	v_log_f32_e32 v6, v1
	v_max_f32_e32 v1, v78, v78
	v_add_f32_e32 v0, 1.0, v0
	v_min_f32_e32 v8, 0, v1
	v_add_f32_e32 v1, 1.0, v2
	v_log_f32_e32 v0, v0
	v_log_f32_e32 v1, v1
	v_exp_f32_e64 v2, -|v79|
	v_max_f32_e32 v5, v63, v63
	v_min_f32_e32 v5, 0, v5
	v_pk_add_f32 v[178:179], v[4:5], v[0:1] neg_lo:[0,1] neg_hi:[0,1]
	v_max_f32_e32 v1, v79, v79
	v_add_f32_e32 v0, 1.0, v2
	v_min_f32_e32 v9, 0, v1
	v_exp_f32_e64 v1, -|v80|
	v_max_f32_e32 v2, v64, v64
	v_log_f32_e32 v7, v0
	v_exp_f32_e64 v0, -|v64|
	v_min_f32_e32 v4, 0, v2
	v_exp_f32_e64 v2, -|v65|
	v_add_f32_e32 v1, 1.0, v1
	v_add_f32_e32 v0, 1.0, v0
	v_log_f32_e32 v138, v1
	v_add_f32_e32 v1, 1.0, v2
	v_log_f32_e32 v0, v0
	v_log_f32_e32 v1, v1
	v_max_f32_e32 v5, v80, v80
	v_max_f32_e32 v2, v65, v65
	v_min_f32_e32 v140, 0, v5
	v_min_f32_e32 v5, 0, v2
	v_pk_add_f32 v[182:183], v[4:5], v[0:1] neg_lo:[0,1] neg_hi:[0,1]
	v_exp_f32_e64 v0, -|v81|
	v_pk_add_f32 v[194:195], v[8:9], v[6:7] neg_lo:[0,1] neg_hi:[0,1]
	v_sub_f32_e32 v49, v183, v65
	v_sub_f32_e32 v14, v182, v64
	v_add_f32_e32 v0, 1.0, v0
	v_log_f32_e32 v139, v0
	v_max_f32_e32 v0, v81, v81
	v_min_f32_e32 v141, 0, v0
	v_sub_f32_e32 v15, v179, v63
	v_pk_add_f32 v[196:197], v[140:141], v[138:139] neg_lo:[0,1] neg_hi:[0,1]
	v_sub_f32_e32 v12, v178, v62
	v_sub_f32_e32 v11, v177, v61
	v_sub_f32_e32 v10, v176, v60
	v_sub_f32_e32 v13, v175, v59
	v_sub_f32_e32 v8, v174, v58
	v_sub_f32_e32 v7, v173, v57
	v_sub_f32_e32 v6, v172, v56
	v_sub_f32_e32 v9, v171, v55
	v_sub_f32_e32 v4, v170, v54
	v_sub_f32_e32 v5, v169, v53
	v_sub_f32_e32 v2, v168, v52
	v_sub_f32_e32 v1, v167, v51
	v_sub_f32_e32 v0, v166, v50
	v_sub_f32_e32 v65, v197, v81
	v_sub_f32_e32 v58, v196, v80
	v_sub_f32_e32 v63, v195, v79
	v_sub_f32_e32 v62, v194, v78
	v_sub_f32_e32 v61, v193, v77
	v_sub_f32_e32 v56, v192, v76
	v_sub_f32_e32 v59, v191, v75
	v_sub_f32_e32 v60, v190, v74
	v_sub_f32_e32 v57, v189, v73
	v_sub_f32_e32 v52, v188, v72
	v_sub_f32_e32 v55, v187, v71
	v_sub_f32_e32 v54, v186, v70
	v_sub_f32_e32 v53, v185, v69
	v_sub_f32_e32 v48, v184, v68
	v_sub_f32_e32 v51, v181, v67
	v_sub_f32_e32 v50, v180, v66
	s_and_saveexec_b64 s[90:91], vcc
	s_cbranch_execz .LBB0_582
; template <int TYPE>
; DI void attn_item(KargPtr p, int b, int h, int qb, unsigned char* smem) {
;     ...
;                 if (k0 + 63 >= qw) {
;                     asm volatile("");
;                     const int rel = myq - k0 - 4 * hh;
; #pragma unroll
;                     for (int i = 0; i < 16; ++i) {
;                         const int off = 8 * (i >> 2) + (i & 3);
;                         if (off >= rel) { lk0[i] = 0.f; s0[i] = -1e30f; }
;                         if (off + 32 >= rel) { lk1[i] = 0.f; s1[i] = -1e30f; }
;                     }
;                 }
	v_cmp_lt_i32_e64 s[68:69], 26, v223
	v_cmp_lt_i32_e64 s[70:71], 27, v223
	v_cmp_lt_i32_e64 s[66:67], 25, v223
	s_or_b64 s[68:69], s[70:71], s[68:69]
	v_cmp_lt_i32_e64 s[64:65], 24, v223
	s_or_b64 s[66:67], s[68:69], s[66:67]
	v_cmp_lt_i32_e64 s[62:63], 19, v223
	s_or_b64 s[64:65], s[66:67], s[64:65]
	v_cmp_lt_i32_e64 s[60:61], 18, v223
	s_or_b64 s[62:63], s[64:65], s[62:63]
	v_cmp_lt_i32_e64 s[58:59], 17, v223
	s_or_b64 s[60:61], s[62:63], s[60:61]
	v_cmp_lt_i32_e64 s[56:57], 16, v223
	s_or_b64 s[58:59], s[60:61], s[58:59]
	v_cmp_lt_i32_e64 s[54:55], 11, v223
	s_or_b64 s[56:57], s[58:59], s[56:57]
	v_cmp_lt_i32_e64 s[52:53], 10, v223
	s_or_b64 s[54:55], s[56:57], s[54:55]
	v_cmp_lt_i32_e64 s[50:51], 9, v223
	s_or_b64 s[52:53], s[54:55], s[52:53]
	v_cmp_lt_i32_e64 s[48:49], 8, v223
	s_or_b64 s[50:51], s[52:53], s[50:51]
	v_cmp_lt_i32_e64 s[46:47], 3, v223
	s_or_b64 s[48:49], s[50:51], s[48:49]
	v_cmp_lt_i32_e64 s[44:45], 2, v223
	s_or_b64 s[46:47], s[48:49], s[46:47]
	v_cmp_lt_i32_e64 s[42:43], 1, v223
	s_or_b64 s[44:45], s[46:47], s[44:45]
	v_cmp_lt_i32_e64 s[38:39], 0, v223
	s_or_b64 s[42:43], s[44:45], s[42:43]
	s_or_b64 s[38:39], s[42:43], s[38:39]
	v_cmp_lt_i32_e64 s[36:37], 58, v223
	v_cndmask_b32_e64 v0, 0, v0, s[38:39]
	v_cndmask_b32_e64 v166, v207, v166, s[38:39]
	v_cmp_lt_i32_e64 s[38:39], 59, v223
	v_cmp_lt_i32_e64 s[34:35], 57, v223
	s_or_b64 s[36:37], s[38:39], s[36:37]
	v_cmp_lt_i32_e64 s[30:31], 56, v223
	s_or_b64 s[34:35], s[36:37], s[34:35]
	v_cmp_lt_i32_e64 s[28:29], 51, v223
	s_or_b64 s[30:31], s[34:35], s[30:31]
	v_cmp_lt_i32_e64 s[26:27], 50, v223
	s_or_b64 s[28:29], s[30:31], s[28:29]
	v_cmp_lt_i32_e64 s[24:25], 49, v223
	s_or_b64 s[26:27], s[28:29], s[26:27]
	v_cmp_lt_i32_e64 s[22:23], 48, v223
	s_or_b64 s[24:25], s[26:27], s[24:25]
	v_cmp_lt_i32_e64 s[20:21], 43, v223
	s_or_b64 s[22:23], s[24:25], s[22:23]
	v_cmp_lt_i32_e64 s[18:19], 42, v223
	s_or_b64 s[20:21], s[22:23], s[20:21]
	v_cmp_lt_i32_e64 s[16:17], 41, v223
	s_or_b64 s[18:19], s[20:21], s[18:19]
	v_cmp_lt_i32_e64 s[14:15], 40, v223
	s_or_b64 s[16:17], s[18:19], s[16:17]
	v_cmp_lt_i32_e64 s[12:13], 35, v223
	s_or_b64 s[14:15], s[16:17], s[14:15]
	v_cmp_lt_i32_e64 s[10:11], 34, v223
	s_or_b64 s[12:13], s[14:15], s[12:13]
	v_cmp_lt_i32_e64 s[8:9], 33, v223
	s_or_b64 s[10:11], s[12:13], s[10:11]
	v_cmp_lt_i32_e32 vcc, 32, v223
	v_cndmask_b32_e64 v14, 0, v14, s[68:69]
	v_cndmask_b32_e64 v182, v207, v182, s[68:69]
	v_readlane_b32 s68, v254, 63
	s_or_b64 s[8:9], s[10:11], s[8:9]
	v_cndmask_b32_e64 v1, 0, v1, s[42:43]
	v_cndmask_b32_e64 v167, v207, v167, s[42:43]
	v_readlane_b32 s42, v255, 17
	v_readlane_b32 s69, v255, 0
	s_or_b64 vcc, s[8:9], vcc
	v_cndmask_b32_e64 v49, 0, v49, s[70:71]
	v_cndmask_b32_e64 v15, 0, v15, s[66:67]
	v_cndmask_b32_e64 v12, 0, v12, s[64:65]
	v_cndmask_b32_e64 v11, 0, v11, s[62:63]
	v_cndmask_b32_e64 v10, 0, v10, s[60:61]
	v_cndmask_b32_e64 v13, 0, v13, s[58:59]
	v_cndmask_b32_e64 v8, 0, v8, s[56:57]
	v_cndmask_b32_e64 v7, 0, v7, s[54:55]
	v_cndmask_b32_e64 v6, 0, v6, s[52:53]
	v_cndmask_b32_e64 v9, 0, v9, s[50:51]
	v_cndmask_b32_e64 v4, 0, v4, s[48:49]
	v_cndmask_b32_e64 v5, 0, v5, s[46:47]
	v_cndmask_b32_e64 v2, 0, v2, s[44:45]
	v_readlane_b32 s43, v255, 18
	v_cndmask_b32_e64 v168, v207, v168, s[44:45]
	v_cndmask_b32_e64 v169, v207, v169, s[46:47]
	v_cndmask_b32_e64 v170, v207, v170, s[48:49]
	v_cndmask_b32_e64 v171, v207, v171, s[50:51]
	v_cndmask_b32_e64 v172, v207, v172, s[52:53]
	v_cndmask_b32_e64 v173, v207, v173, s[54:55]
	v_cndmask_b32_e64 v174, v207, v174, s[56:57]
	v_cndmask_b32_e64 v175, v207, v175, s[58:59]
	v_cndmask_b32_e64 v176, v207, v176, s[60:61]
	v_readlane_b32 s61, v255, 19
	s_mov_b32 s60, 0xc32a0000
	v_cndmask_b32_e64 v177, v207, v177, s[62:63]
	s_movk_i32 s62, 0x1fff
	v_readlane_b32 s63, v255, 1
	v_cndmask_b32_e64 v178, v207, v178, s[64:65]
	s_mov_b32 s65, 0x10000
	v_readlane_b32 s64, v255, 2
	v_cndmask_b32_e64 v179, v207, v179, s[66:67]
	s_mov_b32 s67, 0x18000
	s_movk_i32 s66, 0x6000
	s_mov_b32 s69, 0x8000
	v_cndmask_b32_e64 v183, v207, v183, s[70:71]
	s_mov_b32 s71, 0x800000
	s_mov_b32 s70, 0x24000
	v_cndmask_b32_e64 v65, 0, v65, s[38:39]
	v_cndmask_b32_e64 v58, 0, v58, s[36:37]
	v_cndmask_b32_e64 v63, 0, v63, s[34:35]
	v_cndmask_b32_e64 v62, 0, v62, s[30:31]
	v_cndmask_b32_e64 v61, 0, v61, s[28:29]
	v_cndmask_b32_e64 v56, 0, v56, s[26:27]
	v_cndmask_b32_e64 v59, 0, v59, s[24:25]
	v_cndmask_b32_e64 v60, 0, v60, s[22:23]
	v_cndmask_b32_e64 v57, 0, v57, s[20:21]
	v_cndmask_b32_e64 v52, 0, v52, s[18:19]
	v_cndmask_b32_e64 v55, 0, v55, s[16:17]
	v_cndmask_b32_e64 v54, 0, v54, s[14:15]
	v_cndmask_b32_e64 v53, 0, v53, s[12:13]
	v_cndmask_b32_e64 v48, 0, v48, s[10:11]
	v_cndmask_b32_e64 v51, 0, v51, s[8:9]
	v_cndmask_b32_e32 v50, 0, v50, vcc
	v_cndmask_b32_e32 v180, v207, v180, vcc
	v_cndmask_b32_e64 v181, v207, v181, s[8:9]
	v_cndmask_b32_e64 v184, v207, v184, s[10:11]
	v_cndmask_b32_e64 v185, v207, v185, s[12:13]
	v_cndmask_b32_e64 v186, v207, v186, s[14:15]
	v_cndmask_b32_e64 v187, v207, v187, s[16:17]
	v_cndmask_b32_e64 v188, v207, v188, s[18:19]
	v_cndmask_b32_e64 v189, v207, v189, s[20:21]
	v_cndmask_b32_e64 v190, v207, v190, s[22:23]
	v_cndmask_b32_e64 v191, v207, v191, s[24:25]
	v_cndmask_b32_e64 v192, v207, v192, s[26:27]
	v_readlane_b32 s26, v255, 21
	v_cndmask_b32_e64 v193, v207, v193, s[28:29]
	v_cndmask_b32_e64 v194, v207, v194, s[30:31]
	s_mov_b32 s30, 0x3a800000
	v_cndmask_b32_e64 v195, v207, v195, s[34:35]
	v_cndmask_b32_e64 v196, v207, v196, s[36:37]
	s_mov_b32 s36, 0x358637bd
	v_cndmask_b32_e64 v197, v207, v197, s[38:39]
	s_mov_b64 s[38:39], 0x1000

; #define WAIT_OLD(S) do { if (TYPE == 2) asm volatile("s_waitcnt vmcnt(4)" : "+v"(rk0##S), "+v"(rk1##S), "+v"(rv0##S), "+v"(rv1##S), "+v"(rkr##S), "+v"(rck##S)); \
;         else asm volatile("s_waitcnt vmcnt(5)" : "+v"(rk0##S), "+v"(rk1##S), "+v"(rv0##S), "+v"(rv1##S), "+v"(rkr##S), "+v"(rck##S)); } while (0)
; #define SB_FLAGS(N_) do { if (TYPE != 1) { if (TYPE == 2) wdone = (__all(carry < -170.f) != 0); if (lane == 0) flags[((N_) & 1) * 8 + w8] = wdone ? 1u : 0u; } } while (0)
; template <int TYPE>
; DI void attn_item(KargPtr p, int b, int h, int qb, unsigned char* smem) {
;     ...
;         WAIT_OLD(B);
;         STORE_TILE(B, 0);
;         SB_FLAGS(n + 1);
;         __syncthreads();
;         if (SB_DONE(n + 1)) break;
.LBB0_583:
	s_or_b64 exec, exec, s[82:83]
	v_cmp_gt_f32_e32 vcc, s60, v164
	s_cmp_eq_u64 vcc, exec
	s_waitcnt vmcnt(4)
	s_cselect_b64 s[8:9], -1, 0
	ds_write_b128 v212, v[122:125]
	ds_write_b128 v213, v[126:129]
	ds_write2_b64 v215, v[130:131], v[132:133] offset0:128 offset1:130
	ds_write2_b64 v217, v[134:135], v[136:137] offset0:128 offset1:130
	s_and_saveexec_b64 s[10:11], s[6:7]
	v_cndmask_b32_e64 v0, 0, 1, s[8:9]
	ds_write_b32 v222, v0 offset:32
	s_or_b64 exec, exec, s[10:11]
	v_mov_b32_e32 v0, s96
	s_waitcnt lgkmcnt(0)
	s_barrier
	ds_read_b128 v[4:7], v0
	v_mov_b32_e32 v1, s97
	ds_read_b128 v[226:229], v1
	s_xor_b64 s[10:11], s[88:89], -1
	s_addk_i32 s2, 0xff80
	v_add_u32_e32 v223, 0x80, v223
	s_waitcnt lgkmcnt(0)
	v_and_b32_e32 v0, v5, v4
	v_and_b32_e32 v0, v0, v6
	v_and_b32_e32 v0, v0, v7
	s_add_i32 s78, s33, -1
	s_waitcnt lgkmcnt(0)
	v_and_b32_e32 v0, v0, v226
	v_and_b32_e32 v0, v0, v227
	v_and_b32_e32 v0, v0, v228
	v_and_b32_e32 v0, v0, v229
	v_cmp_ne_u32_e32 vcc, 0, v0
	s_or_b64 s[10:11], vcc, s[10:11]
	s_and_b64 vcc, exec, s[10:11]
	s_cbranch_vccz .LBB0_572

; template <int TYPE>
; DI void attn_item(KargPtr p, int b, int h, int qb, unsigned char* smem) {
;     ...
;         __syncthreads();
;         if (SB_DONE(n)) break;
.LBB0_606:
	s_or_b64 exec, exec, s[10:11]
	v_mov_b32_e32 v0, s2
	s_waitcnt lgkmcnt(0)
	s_barrier
	ds_read_b128 v[48:51], v0
	v_mov_b32_e32 v1, s97
	ds_read_b128 v[226:229], v1
	s_waitcnt lgkmcnt(0)
	v_and_b32_e32 v0, v49, v48
	v_and_b32_e32 v0, v0, v50
	v_and_b32_e32 v0, v0, v51
	s_waitcnt lgkmcnt(0)
	v_and_b32_e32 v0, v0, v226
	v_and_b32_e32 v0, v0, v227
	v_and_b32_e32 v0, v0, v228
	v_and_b32_e32 v0, v0, v229
	v_cmp_ne_u32_e32 vcc, 0, v0
	s_cbranch_vccz .LBB0_608
	s_cbranch_execz .LBB0_620
	s_branch .LBB0_564

; #define SB_FLAGS(N_) do { if (TYPE != 1) { if (TYPE == 2) wdone = (__all(carry < -170.f) != 0); if (lane == 0) flags[((N_) & 1) * 8 + w8] = wdone ? 1u : 0u; } } while (0)
; template <int TYPE>
; DI void attn_item(KargPtr p, int b, int h, int qb, unsigned char* smem) {
;     ...
;         SB_FLAGS(n + 1);
;         __syncthreads();
;         if (SB_DONE(n + 1)) break;
.LBB0_617:
	s_or_b64 exec, exec, s[10:11]
	s_and_saveexec_b64 s[10:11], s[8:9]
	v_and_b32_e32 v0, 0xff, v189
	ds_write_b32 v187, v0 offset:32
	s_or_b64 exec, exec, s[10:11]
	v_mov_b32_e32 v0, s33
	s_waitcnt lgkmcnt(0)
	s_barrier
	ds_read_b128 v[48:51], v0
	v_mov_b32_e32 v1, s79
	ds_read_b128 v[226:229], v1
	s_xor_b64 s[10:11], s[82:83], -1
	v_add_u32_e32 v188, 0x80, v188
	s_addk_i32 s74, 0xff80
	s_waitcnt lgkmcnt(0)
	v_and_b32_e32 v0, v49, v48
	v_and_b32_e32 v0, v0, v50
	v_and_b32_e32 v0, v0, v51
	s_add_i32 s84, s84, -1
	s_waitcnt lgkmcnt(0)
	v_and_b32_e32 v0, v0, v226
	v_and_b32_e32 v0, v0, v227
	v_and_b32_e32 v0, v0, v228
	v_and_b32_e32 v0, v0, v229
	v_cmp_ne_u32_e32 vcc, 0, v0
	s_or_b64 s[10:11], vcc, s[10:11]
	s_and_b64 vcc, exec, s[10:11]
	s_cbranch_vccnz .LBB0_564
